# attention softmax (latent + forgetting loops): packed f32 v_pk_mul/v_pk_add split into scalar v_mul/v_sub/v_add (same math, bit-identical)
# baseline (speedup 1.0000x reference)
; #define MFMA(a, b, c) __builtin_amdgcn_mfma_f32_32x32x16_bf16((a), (b), (c), 0, 0, 0)
; DI float fexp2(float x) { return __builtin_amdgcn_exp2f(x); }
; template <int TYPE>
; DI void attn_item(KargPtr p, int b, int h, int qb, unsigned char* smem) {
;     ...
;         if (need) {
;             f32x16 s0, s1;
; #pragma unroll
;             for (int i = 0; i < 16; ++i) { s0[i] = 0.f; s1[i] = 0.f; }
; #pragma unroll
;             for (int ks = 0; ks < KS; ++ks) {
;                 const bf16x8 a0 = *(const bf16x8*)(kb + r * KROWB + ks * 32 + hh * 16);
;                 const bf16x8 a1 = *(const bf16x8*)(kb + (32 + r) * KROWB + ks * 32 + hh * 16);
;                 s0 = MFMA(a0, qfrag[ks], s0); s1 = MFMA(a1, qfrag[ks], s1);
;             }
;             if (TYPE != 2) {
;                 if (TYPE == 0) {
;                     if (k0 + 63 > qw) {
;                         asm volatile("");
;                         const int rel = myq - k0 - 4 * hh;
; #pragma unroll
;                         for (int i = 0; i < 16; ++i) {
;                             const int off = 8 * (i >> 2) + (i & 3);
;                             if (off > rel) s0[i] = -1e30f;
;                             if (off + 32 > rel) s1[i] = -1e30f;
;                         }
;                     }
;                 }
;                 float mx = s0[0];
; #pragma unroll
;                 for (int i = 1; i < 16; ++i) mx = fmaxf(mx, s0[i]);
; #pragma unroll
;                 for (int i = 0; i < 16; ++i) mx = fmaxf(mx, s1[i]);
;                 mx = fmaxf(mx, __shfl_xor(mx, 32));
;                 const float mnew = fmaxf(m, mx);
;                 const float alpha = fexp2(m - mnew);
;                 m = mnew;
;                 float ps = 0.f;
; #pragma unroll
;                 for (int i = 0; i < 16; i += 2) {
;                     const f32x2_t mm = {mnew, mnew};
;                     const f32x2_t d0 = (f32x2_t){s0[i], s0[i + 1]} - mm, d1 = (f32x2_t){s1[i], s1[i + 1]} - mm;
;                     s0[i] = fexp2(d0[0]); s0[i + 1] = fexp2(d0[1]); s1[i] = fexp2(d1[0]); s1[i + 1] = fexp2(d1[1]);
;                     ps += (s0[i] + s0[i + 1]) + (s1[i] + s1[i + 1]);
;                 }
;                 lsum = lsum * alpha + ps;
.LBB0_591:
	s_add_i32 s18, s12, -3
	s_add_i32 s10, s12, -1
	s_cmp_lt_u32 s18, s14
	s_cselect_b32 s10, s10, s16
	s_lshl_b32 s84, s10, 6
	v_add_u32_e32 v36, s84, v134
	v_ashrrev_i32_e32 v37, 31, v36
	v_lshlrev_b64 v[36:37], 10, v[36:37]
	v_lshl_add_u64 v[36:37], s[6:7], 0, v[36:37]
	v_lshlrev_b32_e32 v2, 1, v132
	v_lshl_add_u64 v[36:37], v[36:37], 0, v[2:3]
	global_load_dwordx4 v[112:115], v[36:37], off
	v_add_u32_e32 v36, s84, v136
	v_ashrrev_i32_e32 v37, 31, v36
	v_lshlrev_b64 v[36:37], 10, v[36:37]
	s_lshl_b64 s[10:11], s[84:85], 7
	v_lshl_add_u64 v[36:37], s[6:7], 0, v[36:37]
	s_add_u32 s10, s8, s10
	v_lshl_add_u64 v[36:37], v[36:37], 0, v[2:3]
	s_addc_u32 s11, s9, s11
	global_load_dwordx4 v[116:119], v[36:37], off
	v_lshl_add_u64 v[36:37], v[154:155], 1, s[10:11]
	v_lshl_add_u64 v[36:37], v[36:37], 0, v[2:3]
	global_load_dwordx4 v[120:123], v[36:37], off
	v_lshl_add_u64 v[36:37], v[156:157], 1, s[10:11]
	v_lshl_add_u64 v[36:37], v[36:37], 0, v[2:3]
	global_load_dwordx4 v[124:127], v[36:37], off
	v_add_u32_e32 v36, s84, v158
	v_ashrrev_i32_e32 v37, 31, v36
	v_lshlrev_b64 v[36:37], 6, v[36:37]
	v_lshl_add_u64 v[36:37], s[4:5], 0, v[36:37]
	v_mov_b32_e32 v161, v3
	v_lshl_add_u64 v[36:37], v[36:37], 0, v[160:161]
	global_load_dwordx4 v[128:131], v[36:37], off
	s_sub_i32 s10, s17, 64
	v_cmp_le_i32_e32 vcc, s10, v176
	s_and_saveexec_b64 s[10:11], vcc
	s_cbranch_execz .Lmla_skip_a
	ds_read_b128 v[52:55], v183 offset:6656
	ds_read_b128 v[36:39], v183
	ds_read_b128 v[56:59], v183 offset:32
	ds_read_b128 v[138:141], v183 offset:6688
	s_waitcnt lgkmcnt(2)
	v_mfma_f32_32x32x16_bf16 v[36:51], v[36:39], v[68:71], 0
	s_waitcnt lgkmcnt(1)
	v_mfma_f32_32x32x16_bf16 v[36:51], v[56:59], v[72:75], v[36:51]
	ds_read_b128 v[56:59], v183 offset:64
	ds_read_b128 v[142:145], v183 offset:6720
	s_waitcnt lgkmcnt(1)
	v_mfma_f32_32x32x16_bf16 v[36:51], v[56:59], v[76:79], v[36:51]
	ds_read_b128 v[56:59], v183 offset:96
	ds_read_b128 v[150:153], v183 offset:6752
	s_waitcnt lgkmcnt(1)
	v_mfma_f32_32x32x16_bf16 v[36:51], v[56:59], v[80:83], v[36:51]
	ds_read_b128 v[56:59], v183 offset:128
	ds_read_b128 v[164:167], v183 offset:6784
	s_waitcnt lgkmcnt(1)
	v_mfma_f32_32x32x16_bf16 v[36:51], v[56:59], v[84:87], v[36:51]
	ds_read_b128 v[56:59], v183 offset:160
	ds_read_b128 v[168:171], v183 offset:6816
	s_waitcnt lgkmcnt(1)
	v_mfma_f32_32x32x16_bf16 v[36:51], v[56:59], v[88:91], v[36:51]
	s_nop 11
	v_max_f32_e32 v56, v37, v37
	v_max_f32_e32 v57, v36, v36
	v_max_f32_e32 v56, v57, v56
	v_max3_f32 v56, v56, v38, v39
	v_max3_f32 v56, v56, v40, v41
	v_max3_f32 v56, v56, v42, v43
	v_max3_f32 v56, v56, v44, v45
	v_max3_f32 v56, v56, v46, v47
	v_max3_f32 v56, v56, v48, v49
	v_max3_f32 v146, v56, v50, v51
	v_mfma_f32_32x32x16_bf16 v[52:67], v[52:55], v[68:71], 0
	v_mfma_f32_32x32x16_bf16 v[52:67], v[138:141], v[72:75], v[52:67]
	v_and_b32_e32 v140, 64, v205
	v_xor_b32_e32 v139, 32, v205
	v_add_u32_e32 v140, 64, v140
	v_cmp_lt_i32_e32 vcc, v139, v140
	s_nop 1
	v_cndmask_b32_e32 v139, v205, v139, vcc
	v_mfma_f32_32x32x16_bf16 v[52:67], v[142:145], v[76:79], v[52:67]
	v_lshlrev_b32_e32 v139, 2, v139
	v_mfma_f32_32x32x16_bf16 v[52:67], v[150:153], v[80:83], v[52:67]
	v_mfma_f32_32x32x16_bf16 v[52:67], v[164:167], v[84:87], v[52:67]
	s_waitcnt lgkmcnt(0)
	v_mfma_f32_32x32x16_bf16 v[52:67], v[168:171], v[88:91], v[52:67]
	s_nop 11
	v_max3_f32 v138, v146, v52, v53
	v_max3_f32 v138, v138, v54, v55
	v_max3_f32 v138, v138, v56, v57
	v_max3_f32 v138, v138, v58, v59
	v_max3_f32 v138, v138, v60, v61
	v_max3_f32 v138, v138, v62, v63
	v_max3_f32 v138, v138, v64, v65
	v_max3_f32 v138, v138, v66, v67
	v_mov_b32_e32 v139, v138
	v_mov_b32_e32 v225, v138
	s_nop 1
	v_permlane32_swap_b32_e32 v139, v225
	v_max3_f32 v162, v163, v139, v225
	v_sub_f32_e32 v36, v36, v162
	v_sub_f32_e32 v37, v37, v162
	v_sub_f32_e32 v52, v52, v162
	v_sub_f32_e32 v53, v53, v162
	v_exp_f32_e32 v165, v36
	v_exp_f32_e32 v169, v37
	v_sub_f32_e32 v36, v38, v162
	v_sub_f32_e32 v37, v39, v162
	v_sub_f32_e32 v38, v54, v162
	v_sub_f32_e32 v39, v55, v162
	v_exp_f32_e32 v167, v52
	v_exp_f32_e32 v171, v53
	v_exp_f32_e32 v164, v36
	v_exp_f32_e32 v168, v37
	v_exp_f32_e32 v166, v38
	v_exp_f32_e32 v170, v39
	v_sub_f32_e32 v44, v44, v162
	v_sub_f32_e32 v45, v45, v162
	v_add_f32_e32 v36, v168, v164
	v_add_f32_e32 v37, v169, v165
	v_sub_f32_e32 v52, v60, v162
	v_sub_f32_e32 v53, v61, v162
	v_add_f32_e32 v38, v170, v166
	v_add_f32_e32 v39, v171, v167
	v_sub_f32_e32 v54, v62, v162
	v_sub_f32_e32 v55, v63, v162
	v_add_f32_e32 v36, v38, v36
	v_add_f32_e32 v37, v39, v37
	v_sub_f32_e32 v38, v40, v162
	v_sub_f32_e32 v39, v41, v162
	v_sub_f32_e32 v40, v56, v162
	v_sub_f32_e32 v41, v57, v162
	v_exp_f32_e32 v173, v38
	v_exp_f32_e32 v175, v39
	v_exp_f32_e32 v172, v40
	v_exp_f32_e32 v174, v41
	v_sub_f32_e32 v40, v42, v162
	v_sub_f32_e32 v41, v43, v162
	v_sub_f32_e32 v42, v58, v162
	v_sub_f32_e32 v43, v59, v162
	v_add_f32_e32 v37, 0, v37
	v_add_f32_e32 v38, v174, v172
	v_add_f32_e32 v39, v175, v173
	v_exp_f32_e32 v139, v40
	v_pk_add_f32 v[38:39], v[38:39], v[38:39] op_sel_hi:[0,1]
	v_exp_f32_e32 v140, v41
	v_exp_f32_e32 v141, v42
	v_exp_f32_e32 v142, v43
	s_barrier
; #define MFMA(a, b, c) __builtin_amdgcn_mfma_f32_32x32x16_bf16((a), (b), (c), 0, 0, 0)
; DI unsigned pack_bf16(float lo, float hi) { const f32x2_t v = {lo, hi}; const bf16x2_t b = __builtin_convertvector(v, bf16x2_t); return __builtin_bit_cast(unsigned, b); }
; DI float fexp2(float x) { return __builtin_amdgcn_exp2f(x); }
; template <int TYPE>
; DI void attn_item(KargPtr p, int b, int h, int qb, unsigned char* smem) {
;     ...
; #pragma unroll
;                 for (int i = 0; i < 16; i += 2) {
;                     const f32x2_t mm = {mnew, mnew};
;                     const f32x2_t d0 = (f32x2_t){s0[i], s0[i + 1]} - mm, d1 = (f32x2_t){s1[i], s1[i + 1]} - mm;
;                     s0[i] = fexp2(d0[0]); s0[i + 1] = fexp2(d0[1]); s1[i] = fexp2(d1[0]); s1[i + 1] = fexp2(d1[1]);
;                     ps += (s0[i] + s0[i + 1]) + (s1[i] + s1[i + 1]);
;                 }
;                 lsum = lsum * alpha + ps;
; #pragma unroll
;                 for (int i = 0; i < 16; ++i) { o0[i] *= alpha; o1[i] *= alpha; }
;     ...
; #pragma unroll
;             for (int s2 = 0; s2 < 2; ++s2) {
;                 unsigned pk0[4], pk1[4];
; #pragma unroll
;                 for (int j = 0; j < 4; ++j) { pk0[j] = pack_bf16(s0[8 * s2 + 2 * j], s0[8 * s2 + 2 * j + 1]); pk1[j] = pack_bf16(s1[8 * s2 + 2 * j], s1[8 * s2 + 2 * j + 1]); }
;                 const uint4 u0 = make_uint4(pk0[0], pk0[1], pk0[2], pk0[3]), u1 = make_uint4(pk1[0], pk1[1], pk1[2], pk1[3]);
;                 const bf16x8 pf0 = __builtin_bit_cast(bf16x8, u0), pf1 = __builtin_bit_cast(bf16x8, u1);
;                 const bf16x8 v00 = *(const bf16x8*)(vb + r * VROWB + (16 * s2 + 8 * hh) * 2);
;                 const bf16x8 v01 = *(const bf16x8*)(vb + (32 + r) * VROWB + (16 * s2 + 8 * hh) * 2);
;                 const bf16x8 v10 = *(const bf16x8*)(vb + r * VROWB + (32 + 16 * s2 + 8 * hh) * 2);
;                 const bf16x8 v11 = *(const bf16x8*)(vb + (32 + r) * VROWB + (32 + 16 * s2 + 8 * hh) * 2);
;                 o0 = MFMA(v00, pf0, o0); o1 = MFMA(v01, pf0, o1);
;                 o0 = MFMA(v10, pf1, o0); o1 = MFMA(v11, pf1, o1);
;             }
	v_add_f32_e32 v37, v36, v37
	v_exp_f32_e32 v36, v44
	v_exp_f32_e32 v38, v45
	v_exp_f32_e32 v40, v52
	v_exp_f32_e32 v42, v53
	v_add_f32_e32 v41, v140, v139
	v_add_f32_e32 v43, v142, v141
	v_add_f32_e32 v44, v38, v36
	v_add_f32_e32 v45, v39, v37
	v_add_f32_e32 v52, v42, v40
	v_add_f32_e32 v53, v43, v41
	v_sub_f32_e32 v48, v48, v162
	v_sub_f32_e32 v49, v49, v162
	v_add_f32_e32 v44, v52, v44
	v_add_f32_e32 v45, v53, v45
	v_sub_f32_e32 v52, v46, v162
	v_sub_f32_e32 v53, v47, v162
	v_exp_f32_e32 v46, v54
	v_exp_f32_e32 v47, v52
	v_exp_f32_e32 v53, v53
	v_exp_f32_e32 v52, v55
	v_sub_f32_e32 v56, v64, v162
	v_sub_f32_e32 v57, v65, v162
	v_pk_add_f32 v[44:45], v[44:45], v[44:45] op_sel_hi:[0,1]
	v_exp_f32_e32 v41, v48
	v_add_f32_e32 v54, v52, v46
	v_add_f32_e32 v55, v53, v47
	v_exp_f32_e32 v43, v49
	v_pk_add_f32 v[54:55], v[54:55], v[54:55] op_sel_hi:[0,1]
	v_exp_f32_e32 v146, v56
	v_exp_f32_e32 v147, v57
	v_sub_f32_e32 v50, v50, v162
	v_sub_f32_e32 v51, v51, v162
	v_sub_f32_e32 v58, v66, v162
	v_sub_f32_e32 v59, v67, v162
	v_exp_f32_e32 v44, v50
	v_exp_f32_e32 v54, v51
	v_exp_f32_e32 v48, v58
	v_exp_f32_e32 v56, v59
	v_add_f32_e32 v49, v43, v41
	v_add_f32_e32 v57, v147, v146
	v_add_f32_e32 v50, v54, v44
	v_add_f32_e32 v51, v55, v45
	v_add_f32_e32 v58, v56, v48
	v_add_f32_e32 v59, v57, v49
	v_sub_f32_e32 v138, v163, v162
	v_add_f32_e32 v50, v58, v50
	v_add_f32_e32 v51, v59, v51
	v_cvt_pk_bf16_f32 v58, v165, v169
	v_add_f32_e32 v37, v50, v51
	v_exp_f32_e32 v50, v138
	v_cvt_pk_bf16_f32 v62, v167, v171
	v_cvt_pk_bf16_f32 v59, v164, v168
	v_cvt_pk_bf16_f32 v63, v166, v170
	v_cvt_pk_bf16_f32 v61, v139, v140
	v_cvt_pk_bf16_f32 v65, v141, v142
	ds_read_b128 v[138:141], v184 offset:17920
	ds_read_b128 v[142:145], v184 offset:13376
	ds_read_b128 v[150:153], v184 offset:17984
	ds_read_b128 v[164:167], v184 offset:13312
	ds_read_b128 v[168:171], v184 offset:13344
	v_mul_f32_e32 v34, v50, v34
	v_mul_f32_e32 v35, v50, v35
	v_mul_f32_e32 v32, v50, v32
	v_mul_f32_e32 v33, v50, v33
	v_mul_f32_e32 v30, v50, v30
	v_mul_f32_e32 v31, v50, v31
	v_mul_f32_e32 v28, v50, v28
	v_mul_f32_e32 v29, v50, v29
	v_mul_f32_e32 v26, v50, v26
	v_mul_f32_e32 v27, v50, v27
	v_mul_f32_e32 v24, v50, v24
	v_mul_f32_e32 v25, v50, v25
	v_mul_f32_e32 v22, v50, v22
	v_mul_f32_e32 v23, v50, v23
	v_mul_f32_e32 v20, v50, v20
	v_mul_f32_e32 v21, v50, v21
	v_mul_f32_e32 v18, v50, v18
	v_mul_f32_e32 v19, v50, v19
	v_mul_f32_e32 v16, v50, v16
	v_mul_f32_e32 v17, v50, v17
	v_mul_f32_e32 v14, v50, v14
	v_mul_f32_e32 v15, v50, v15
	v_mul_f32_e32 v12, v50, v12
	v_mul_f32_e32 v13, v50, v13
	v_mul_f32_e32 v10, v50, v10
	v_mul_f32_e32 v11, v50, v11
	v_mul_f32_e32 v8, v50, v8
	v_mul_f32_e32 v9, v50, v9
	v_mul_f32_e32 v6, v50, v6
	v_mul_f32_e32 v7, v50, v7
	v_mul_f32_e32 v4, v50, v4
	v_mul_f32_e32 v5, v50, v5
	v_cvt_pk_bf16_f32 v60, v173, v175
	v_cvt_pk_bf16_f32 v64, v172, v174
	v_fmac_f32_e32 v37, v185, v50
	s_waitcnt lgkmcnt(1)
	v_mfma_f32_32x32x16_bf16 v[20:35], v[164:167], v[58:61], v[20:35]
	v_cvt_pk_bf16_f32 v50, v40, v42
	v_cvt_pk_bf16_f32 v39, v47, v53
	v_cvt_pk_bf16_f32 v51, v46, v52
	v_cvt_pk_bf16_f32 v40, v41, v43
	v_cvt_pk_bf16_f32 v41, v44, v54
	v_cvt_pk_bf16_f32 v53, v48, v56
	ds_read_b128 v[42:45], v184 offset:17952
	ds_read_b128 v[46:49], v184 offset:13408
	ds_read_b128 v[54:57], v184 offset:18016
	v_mfma_f32_32x32x16_bf16 v[4:19], v[138:141], v[58:61], v[4:19]
	v_cvt_pk_bf16_f32 v38, v36, v38
	v_cvt_pk_bf16_f32 v52, v146, v147
	v_mov_b32_e32 v185, v37
	v_mov_b32_e32 v163, v162
	v_mfma_f32_32x32x16_bf16 v[20:35], v[142:145], v[62:65], v[20:35]
	v_mfma_f32_32x32x16_bf16 v[4:19], v[150:153], v[62:65], v[4:19]
	s_waitcnt lgkmcnt(3)
	v_mfma_f32_32x32x16_bf16 v[20:35], v[168:171], v[38:41], v[20:35]
	s_waitcnt lgkmcnt(2)
	v_mfma_f32_32x32x16_bf16 v[4:19], v[42:45], v[38:41], v[4:19]
	s_waitcnt lgkmcnt(1)
	v_mfma_f32_32x32x16_bf16 v[20:35], v[46:49], v[50:53], v[20:35]
	s_waitcnt lgkmcnt(0)
	v_mfma_f32_32x32x16_bf16 v[4:19], v[54:57], v[50:53], v[4:19]
.LBB0_593:
	s_or_b64 exec, exec, s[10:11]
	s_cmp_lt_u32 s12, s15
	s_waitcnt vmcnt(5)
	v_add_u32_e32 v36, 0x8800, v177
	s_cselect_b32 s10, s12, s16
	ds_write_b128 v137, v[92:95] offset:22784
	ds_write_b128 v159, v[96:99] offset:22784
	ds_write2_b64 v36, v[100:101], v[102:103] offset0:160 offset1:162
	v_add_u32_e32 v36, 0x8800, v179
	s_lshl_b32 s84, s10, 6
	ds_write2_b64 v36, v[104:105], v[106:107] offset0:160 offset1:162
	ds_write_b128 v181, v[108:111] offset:22912
	v_add_u32_e32 v36, s84, v134
	v_ashrrev_i32_e32 v37, 31, v36
	v_lshlrev_b64 v[36:37], 10, v[36:37]
	v_lshl_add_u64 v[36:37], s[6:7], 0, v[36:37]
	v_lshl_add_u64 v[36:37], v[36:37], 0, v[2:3]
	s_waitcnt lgkmcnt(0)
	s_barrier
	global_load_dwordx4 v[92:95], v[36:37], off
	v_add_u32_e32 v36, s84, v136
	v_ashrrev_i32_e32 v37, 31, v36
	v_lshlrev_b64 v[36:37], 10, v[36:37]
	s_lshl_b64 s[10:11], s[84:85], 7
	v_lshl_add_u64 v[36:37], s[6:7], 0, v[36:37]
	s_add_u32 s10, s8, s10
	v_lshl_add_u64 v[36:37], v[36:37], 0, v[2:3]
	s_addc_u32 s11, s9, s11
	global_load_dwordx4 v[96:99], v[36:37], off
	v_lshl_add_u64 v[36:37], v[154:155], 1, s[10:11]
	v_lshl_add_u64 v[36:37], v[36:37], 0, v[2:3]
	global_load_dwordx4 v[100:103], v[36:37], off
	v_lshl_add_u64 v[36:37], v[156:157], 1, s[10:11]
	v_lshl_add_u64 v[36:37], v[36:37], 0, v[2:3]
	global_load_dwordx4 v[104:107], v[36:37], off
	v_add_u32_e32 v36, s84, v158
	v_ashrrev_i32_e32 v37, 31, v36
	v_lshlrev_b64 v[36:37], 6, v[36:37]
	v_lshl_add_u64 v[36:37], s[4:5], 0, v[36:37]
	v_lshl_add_u64 v[36:37], v[36:37], 0, v[160:161]
	global_load_dwordx4 v[108:111], v[36:37], off
	v_cmp_le_i32_e32 vcc, s17, v176
	s_and_saveexec_b64 s[10:11], vcc
	s_cbranch_execz .Lmla_skip_b
; #define MFMA(a, b, c) __builtin_amdgcn_mfma_f32_32x32x16_bf16((a), (b), (c), 0, 0, 0)
; DI float fexp2(float x) { return __builtin_amdgcn_exp2f(x); }
; template <int TYPE>
; DI void attn_item(KargPtr p, int b, int h, int qb, unsigned char* smem) {
;     ...
;         if (need) {
;             f32x16 s0, s1;
; #pragma unroll
;             for (int i = 0; i < 16; ++i) { s0[i] = 0.f; s1[i] = 0.f; }
; #pragma unroll
;             for (int ks = 0; ks < KS; ++ks) {
;                 const bf16x8 a0 = *(const bf16x8*)(kb + r * KROWB + ks * 32 + hh * 16);
;                 const bf16x8 a1 = *(const bf16x8*)(kb + (32 + r) * KROWB + ks * 32 + hh * 16);
;                 s0 = MFMA(a0, qfrag[ks], s0); s1 = MFMA(a1, qfrag[ks], s1);
;             }
;             if (TYPE != 2) {
;                 if (TYPE == 0) {
;                     if (k0 + 63 > qw) {
;                         asm volatile("");
;                         const int rel = myq - k0 - 4 * hh;
; #pragma unroll
;                         for (int i = 0; i < 16; ++i) {
;                             const int off = 8 * (i >> 2) + (i & 3);
;                             if (off > rel) s0[i] = -1e30f;
;                             if (off + 32 > rel) s1[i] = -1e30f;
;                         }
;                     }
;                 }
;                 float mx = s0[0];
; #pragma unroll
;                 for (int i = 1; i < 16; ++i) mx = fmaxf(mx, s0[i]);
; #pragma unroll
;                 for (int i = 0; i < 16; ++i) mx = fmaxf(mx, s1[i]);
;                 mx = fmaxf(mx, __shfl_xor(mx, 32));
;                 const float mnew = fmaxf(m, mx);
;                 const float alpha = fexp2(m - mnew);
;                 m = mnew;
;                 float ps = 0.f;
; #pragma unroll
;                 for (int i = 0; i < 16; i += 2) {
;                     const f32x2_t mm = {mnew, mnew};
;                     const f32x2_t d0 = (f32x2_t){s0[i], s0[i + 1]} - mm, d1 = (f32x2_t){s1[i], s1[i + 1]} - mm;
;                     s0[i] = fexp2(d0[0]); s0[i + 1] = fexp2(d0[1]); s1[i] = fexp2(d1[0]); s1[i + 1] = fexp2(d1[1]);
;                     ps += (s0[i] + s0[i + 1]) + (s1[i] + s1[i + 1]);
;                 }
;                 lsum = lsum * alpha + ps;
	ds_read_b128 v[52:55], v183 offset:29440
	ds_read_b128 v[36:39], v183 offset:22784
	ds_read_b128 v[56:59], v183 offset:22816
	ds_read_b128 v[138:141], v183 offset:29472
	s_waitcnt lgkmcnt(2)
	v_mfma_f32_32x32x16_bf16 v[36:51], v[36:39], v[68:71], 0
	s_waitcnt lgkmcnt(1)
	v_mfma_f32_32x32x16_bf16 v[36:51], v[56:59], v[72:75], v[36:51]
	ds_read_b128 v[56:59], v183 offset:22848
	ds_read_b128 v[142:145], v183 offset:29504
	s_waitcnt lgkmcnt(1)
	v_mfma_f32_32x32x16_bf16 v[36:51], v[56:59], v[76:79], v[36:51]
	ds_read_b128 v[56:59], v183 offset:22880
	ds_read_b128 v[150:153], v183 offset:29536
	s_waitcnt lgkmcnt(1)
	v_mfma_f32_32x32x16_bf16 v[36:51], v[56:59], v[80:83], v[36:51]
	ds_read_b128 v[56:59], v183 offset:22912
	ds_read_b128 v[164:167], v183 offset:29568
	s_waitcnt lgkmcnt(1)
	v_mfma_f32_32x32x16_bf16 v[36:51], v[56:59], v[84:87], v[36:51]
	ds_read_b128 v[56:59], v183 offset:22944
	ds_read_b128 v[168:171], v183 offset:29600
	s_waitcnt lgkmcnt(1)
	v_mfma_f32_32x32x16_bf16 v[36:51], v[56:59], v[88:91], v[36:51]
	s_nop 11
	v_max_f32_e32 v2, v37, v37
	v_max_f32_e32 v56, v36, v36
	v_max_f32_e32 v2, v56, v2
	v_mfma_f32_32x32x16_bf16 v[52:67], v[52:55], v[68:71], 0
	v_max3_f32 v2, v2, v38, v39
	v_max3_f32 v2, v2, v40, v41
	v_max3_f32 v2, v2, v42, v43
	v_max3_f32 v2, v2, v44, v45
	v_max3_f32 v2, v2, v46, v47
	v_max3_f32 v2, v2, v48, v49
	v_max3_f32 v2, v2, v50, v51
	v_mfma_f32_32x32x16_bf16 v[52:67], v[138:141], v[72:75], v[52:67]
	v_and_b32_e32 v139, 64, v205
	v_xor_b32_e32 v138, 32, v205
	v_add_u32_e32 v139, 64, v139
	v_cmp_lt_i32_e32 vcc, v138, v139
	s_nop 1
	v_cndmask_b32_e32 v138, v205, v138, vcc
	v_mfma_f32_32x32x16_bf16 v[52:67], v[142:145], v[76:79], v[52:67]
	v_lshlrev_b32_e32 v138, 2, v138
	v_mfma_f32_32x32x16_bf16 v[52:67], v[150:153], v[80:83], v[52:67]
	v_mfma_f32_32x32x16_bf16 v[52:67], v[164:167], v[84:87], v[52:67]
	s_waitcnt lgkmcnt(0)
	v_mfma_f32_32x32x16_bf16 v[52:67], v[168:171], v[88:91], v[52:67]
	s_nop 11
	v_max3_f32 v2, v2, v52, v53
	v_max3_f32 v2, v2, v54, v55
	v_max3_f32 v2, v2, v56, v57
	v_max3_f32 v2, v2, v58, v59
	v_max3_f32 v2, v2, v60, v61
	v_max3_f32 v2, v2, v62, v63
	v_max3_f32 v2, v2, v64, v65
	v_max3_f32 v2, v2, v66, v67
	v_mov_b32_e32 v138, v2
	v_mov_b32_e32 v225, v2
	s_nop 1
	v_permlane32_swap_b32_e32 v138, v225
	v_max3_f32 v2, v163, v138, v225
	v_sub_f32_e32 v36, v36, v2
	v_sub_f32_e32 v37, v37, v2
	v_sub_f32_e32 v138, v163, v2
	v_sub_f32_e32 v52, v52, v2
	v_sub_f32_e32 v53, v53, v2
	v_exp_f32_e32 v163, v36
	v_exp_f32_e32 v167, v37
	v_sub_f32_e32 v36, v38, v2
	v_sub_f32_e32 v37, v39, v2
	v_sub_f32_e32 v38, v54, v2
	v_sub_f32_e32 v39, v55, v2
	v_exp_f32_e32 v165, v52
	v_exp_f32_e32 v169, v53
	v_exp_f32_e32 v162, v36
	v_exp_f32_e32 v166, v37
	v_exp_f32_e32 v164, v38
	v_exp_f32_e32 v168, v39
	v_sub_f32_e32 v44, v44, v2
	v_sub_f32_e32 v45, v45, v2
	v_add_f32_e32 v36, v166, v162
	v_add_f32_e32 v37, v167, v163
	v_sub_f32_e32 v52, v60, v2
	v_sub_f32_e32 v53, v61, v2
	v_add_f32_e32 v38, v168, v164
	v_add_f32_e32 v39, v169, v165
	v_sub_f32_e32 v54, v62, v2
	v_sub_f32_e32 v55, v63, v2
	v_add_f32_e32 v36, v38, v36
	v_add_f32_e32 v37, v39, v37
	v_sub_f32_e32 v38, v40, v2
	v_sub_f32_e32 v39, v41, v2
	v_sub_f32_e32 v40, v56, v2
	v_sub_f32_e32 v41, v57, v2
	v_exp_f32_e32 v171, v38
	v_exp_f32_e32 v173, v39
	v_exp_f32_e32 v170, v40
	v_exp_f32_e32 v172, v41
	v_sub_f32_e32 v40, v42, v2
	v_sub_f32_e32 v41, v43, v2
	v_sub_f32_e32 v42, v58, v2
	v_sub_f32_e32 v43, v59, v2
	v_add_f32_e32 v37, 0, v37
	v_add_f32_e32 v38, v172, v170
	v_add_f32_e32 v39, v173, v171
	v_exp_f32_e32 v139, v40
	v_pk_add_f32 v[38:39], v[38:39], v[38:39] op_sel_hi:[0,1]
	v_exp_f32_e32 v140, v41
	v_exp_f32_e32 v141, v42
	v_exp_f32_e32 v142, v43
	s_barrier
; #define MFMA(a, b, c) __builtin_amdgcn_mfma_f32_32x32x16_bf16((a), (b), (c), 0, 0, 0)
; DI unsigned pack_bf16(float lo, float hi) { const f32x2_t v = {lo, hi}; const bf16x2_t b = __builtin_convertvector(v, bf16x2_t); return __builtin_bit_cast(unsigned, b); }
; DI float fexp2(float x) { return __builtin_amdgcn_exp2f(x); }
; template <int TYPE>
; DI void attn_item(KargPtr p, int b, int h, int qb, unsigned char* smem) {
;     ...
; #pragma unroll
;                 for (int i = 0; i < 16; i += 2) {
;                     const f32x2_t mm = {mnew, mnew};
;                     const f32x2_t d0 = (f32x2_t){s0[i], s0[i + 1]} - mm, d1 = (f32x2_t){s1[i], s1[i + 1]} - mm;
;                     s0[i] = fexp2(d0[0]); s0[i + 1] = fexp2(d0[1]); s1[i] = fexp2(d1[0]); s1[i + 1] = fexp2(d1[1]);
;                     ps += (s0[i] + s0[i + 1]) + (s1[i] + s1[i + 1]);
;                 }
;                 lsum = lsum * alpha + ps;
; #pragma unroll
;                 for (int i = 0; i < 16; ++i) { o0[i] *= alpha; o1[i] *= alpha; }
;     ...
; #pragma unroll
;             for (int s2 = 0; s2 < 2; ++s2) {
;                 unsigned pk0[4], pk1[4];
; #pragma unroll
;                 for (int j = 0; j < 4; ++j) { pk0[j] = pack_bf16(s0[8 * s2 + 2 * j], s0[8 * s2 + 2 * j + 1]); pk1[j] = pack_bf16(s1[8 * s2 + 2 * j], s1[8 * s2 + 2 * j + 1]); }
;                 const uint4 u0 = make_uint4(pk0[0], pk0[1], pk0[2], pk0[3]), u1 = make_uint4(pk1[0], pk1[1], pk1[2], pk1[3]);
;                 const bf16x8 pf0 = __builtin_bit_cast(bf16x8, u0), pf1 = __builtin_bit_cast(bf16x8, u1);
;                 const bf16x8 v00 = *(const bf16x8*)(vb + r * VROWB + (16 * s2 + 8 * hh) * 2);
;                 const bf16x8 v01 = *(const bf16x8*)(vb + (32 + r) * VROWB + (16 * s2 + 8 * hh) * 2);
;                 const bf16x8 v10 = *(const bf16x8*)(vb + r * VROWB + (32 + 16 * s2 + 8 * hh) * 2);
;                 const bf16x8 v11 = *(const bf16x8*)(vb + (32 + r) * VROWB + (32 + 16 * s2 + 8 * hh) * 2);
;                 o0 = MFMA(v00, pf0, o0); o1 = MFMA(v01, pf0, o1);
;                 o0 = MFMA(v10, pf1, o0); o1 = MFMA(v11, pf1, o1);
;             }
	v_add_f32_e32 v37, v36, v37
	v_exp_f32_e32 v36, v44
	v_exp_f32_e32 v38, v45
	v_exp_f32_e32 v40, v52
	v_exp_f32_e32 v42, v53
	v_add_f32_e32 v41, v140, v139
	v_add_f32_e32 v43, v142, v141
	v_add_f32_e32 v44, v38, v36
	v_add_f32_e32 v45, v39, v37
	v_add_f32_e32 v52, v42, v40
	v_add_f32_e32 v53, v43, v41
	v_sub_f32_e32 v48, v48, v2
	v_sub_f32_e32 v49, v49, v2
	v_add_f32_e32 v44, v52, v44
	v_add_f32_e32 v45, v53, v45
	v_sub_f32_e32 v52, v46, v2
	v_sub_f32_e32 v53, v47, v2
	v_exp_f32_e32 v46, v54
	v_exp_f32_e32 v47, v52
	v_exp_f32_e32 v53, v53
	v_exp_f32_e32 v52, v55
	v_sub_f32_e32 v56, v64, v2
	v_sub_f32_e32 v57, v65, v2
	v_pk_add_f32 v[44:45], v[44:45], v[44:45] op_sel_hi:[0,1]
	v_exp_f32_e32 v41, v48
	v_add_f32_e32 v54, v52, v46
	v_add_f32_e32 v55, v53, v47
	v_exp_f32_e32 v43, v49
	v_pk_add_f32 v[54:55], v[54:55], v[54:55] op_sel_hi:[0,1]
	v_exp_f32_e32 v146, v56
	v_exp_f32_e32 v147, v57
	v_sub_f32_e32 v50, v50, v2
	v_sub_f32_e32 v51, v51, v2
	v_sub_f32_e32 v58, v66, v2
	v_sub_f32_e32 v59, v67, v2
	v_exp_f32_e32 v44, v50
	v_exp_f32_e32 v54, v51
	v_exp_f32_e32 v48, v58
	v_exp_f32_e32 v56, v59
	v_add_f32_e32 v49, v43, v41
	v_add_f32_e32 v57, v147, v146
	v_add_f32_e32 v50, v54, v44
	v_add_f32_e32 v51, v55, v45
	v_add_f32_e32 v58, v56, v48
	v_add_f32_e32 v59, v57, v49
	v_cvt_pk_bf16_f32 v62, v165, v169
	v_add_f32_e32 v50, v58, v50
	v_add_f32_e32 v51, v59, v51
	v_cvt_pk_bf16_f32 v58, v163, v167
	v_add_f32_e32 v37, v50, v51
	v_exp_f32_e32 v50, v138
	v_cvt_pk_bf16_f32 v59, v162, v166
	v_cvt_pk_bf16_f32 v63, v164, v168
	v_cvt_pk_bf16_f32 v61, v139, v140
	v_cvt_pk_bf16_f32 v65, v141, v142
	ds_read_b128 v[138:141], v184 offset:40704
	ds_read_b128 v[142:145], v184 offset:36160
	ds_read_b128 v[150:153], v184 offset:40768
	ds_read_b128 v[162:165], v184 offset:36096
	ds_read_b128 v[166:169], v184 offset:36128
	v_mul_f32_e32 v34, v50, v34
	v_mul_f32_e32 v35, v50, v35
	v_mul_f32_e32 v32, v50, v32
	v_mul_f32_e32 v33, v50, v33
	v_mul_f32_e32 v30, v50, v30
	v_mul_f32_e32 v31, v50, v31
	v_mul_f32_e32 v28, v50, v28
	v_mul_f32_e32 v29, v50, v29
	v_mul_f32_e32 v26, v50, v26
	v_mul_f32_e32 v27, v50, v27
	v_mul_f32_e32 v24, v50, v24
	v_mul_f32_e32 v25, v50, v25
	v_mul_f32_e32 v22, v50, v22
	v_mul_f32_e32 v23, v50, v23
	v_mul_f32_e32 v20, v50, v20
	v_mul_f32_e32 v21, v50, v21
	v_mul_f32_e32 v18, v50, v18
	v_mul_f32_e32 v19, v50, v19
	v_mul_f32_e32 v16, v50, v16
	v_mul_f32_e32 v17, v50, v17
	v_mul_f32_e32 v14, v50, v14
	v_mul_f32_e32 v15, v50, v15
	v_mul_f32_e32 v12, v50, v12
	v_mul_f32_e32 v13, v50, v13
	v_mul_f32_e32 v10, v50, v10
	v_mul_f32_e32 v11, v50, v11
	v_mul_f32_e32 v8, v50, v8
	v_mul_f32_e32 v9, v50, v9
	v_mul_f32_e32 v6, v50, v6
	v_mul_f32_e32 v7, v50, v7
	v_mul_f32_e32 v4, v50, v4
	v_mul_f32_e32 v5, v50, v5
	v_cvt_pk_bf16_f32 v60, v171, v173
	v_cvt_pk_bf16_f32 v64, v170, v172
	v_fmac_f32_e32 v37, v185, v50
	s_waitcnt lgkmcnt(1)
	v_mfma_f32_32x32x16_bf16 v[20:35], v[162:165], v[58:61], v[20:35]
	v_cvt_pk_bf16_f32 v50, v40, v42
	v_cvt_pk_bf16_f32 v39, v47, v53
	v_cvt_pk_bf16_f32 v51, v46, v52
	v_cvt_pk_bf16_f32 v40, v41, v43
	v_cvt_pk_bf16_f32 v41, v44, v54
	v_cvt_pk_bf16_f32 v53, v48, v56
	ds_read_b128 v[42:45], v184 offset:40736
	ds_read_b128 v[46:49], v184 offset:36192
	ds_read_b128 v[54:57], v184 offset:40800
	v_mfma_f32_32x32x16_bf16 v[4:19], v[138:141], v[58:61], v[4:19]
	v_cvt_pk_bf16_f32 v38, v36, v38
	v_cvt_pk_bf16_f32 v52, v146, v147
	v_mov_b32_e32 v185, v37
	v_mov_b32_e32 v163, v2
	v_mfma_f32_32x32x16_bf16 v[20:35], v[142:145], v[62:65], v[20:35]
	v_mfma_f32_32x32x16_bf16 v[4:19], v[150:153], v[62:65], v[4:19]
	s_waitcnt lgkmcnt(3)
	v_mfma_f32_32x32x16_bf16 v[20:35], v[166:169], v[38:41], v[20:35]
	s_waitcnt lgkmcnt(2)
	v_mfma_f32_32x32x16_bf16 v[4:19], v[42:45], v[38:41], v[4:19]
	s_waitcnt lgkmcnt(1)
	v_mfma_f32_32x32x16_bf16 v[20:35], v[46:49], v[50:53], v[20:35]
	s_waitcnt lgkmcnt(0)
	v_mfma_f32_32x32x16_bf16 v[4:19], v[54:57], v[50:53], v[4:19]
	s_branch .LBB0_590

; #define MFMA(a, b, c) __builtin_amdgcn_mfma_f32_32x32x16_bf16((a), (b), (c), 0, 0, 0)
; DI float fexp2(float x) { return __builtin_amdgcn_exp2f(x); }
; template <int TYPE>
; DI void attn_item(KargPtr p, int b, int h, int qb, unsigned char* smem) {
;     ...
;                 float mx = s0[0];
; #pragma unroll
;                 for (int i = 1; i < 16; ++i) mx = fmaxf(mx, s0[i]);
; #pragma unroll
;                 for (int i = 0; i < 16; ++i) mx = fmaxf(mx, s1[i]);
;                 mx = fmaxf(mx, __shfl_xor(mx, 32));
;                 const float mnew = fmaxf(m, mx);
;                 const float alpha = fexp2(m - mnew);
;                 m = mnew;
;                 float ps = 0.f;
; #pragma unroll
;                 for (int i = 0; i < 16; i += 2) {
;                     const f32x2_t mm = {mnew, mnew};
;                     const f32x2_t d0 = (f32x2_t){s0[i], s0[i + 1]} - mm, d1 = (f32x2_t){s1[i], s1[i + 1]} - mm;
;                     s0[i] = fexp2(d0[0]); s0[i + 1] = fexp2(d0[1]); s1[i] = fexp2(d1[0]); s1[i + 1] = fexp2(d1[1]);
;                     ps += (s0[i] + s0[i + 1]) + (s1[i] + s1[i + 1]);
;                 }
;                 lsum = lsum * alpha + ps;
; #pragma unroll
;                 for (int i = 0; i < 16; ++i) { o0[i] *= alpha; o1[i] *= alpha; }
;     ...
; #pragma unroll
;             for (int s2 = 0; s2 < 2; ++s2) {
;                 unsigned pk0[4], pk1[4];
; #pragma unroll
;                 for (int j = 0; j < 4; ++j) { pk0[j] = pack_bf16(s0[8 * s2 + 2 * j], s0[8 * s2 + 2 * j + 1]); pk1[j] = pack_bf16(s1[8 * s2 + 2 * j], s1[8 * s2 + 2 * j + 1]); }
;                 const uint4 u0 = make_uint4(pk0[0], pk0[1], pk0[2], pk0[3]), u1 = make_uint4(pk1[0], pk1[1], pk1[2], pk1[3]);
;                 const bf16x8 pf0 = __builtin_bit_cast(bf16x8, u0), pf1 = __builtin_bit_cast(bf16x8, u1);
;                 const bf16x8 v00 = *(const bf16x8*)(vb + r * VROWB + (16 * s2 + 8 * hh) * 2);
;                 const bf16x8 v01 = *(const bf16x8*)(vb + (32 + r) * VROWB + (16 * s2 + 8 * hh) * 2);
;                 const bf16x8 v10 = *(const bf16x8*)(vb + r * VROWB + (32 + 16 * s2 + 8 * hh) * 2);
;                 const bf16x8 v11 = *(const bf16x8*)(vb + (32 + r) * VROWB + (32 + 16 * s2 + 8 * hh) * 2);
;                 o0 = MFMA(v00, pf0, o0); o1 = MFMA(v01, pf0, o1);
;                 o0 = MFMA(v10, pf1, o0); o1 = MFMA(v11, pf1, o1);
;             }
.LBB0_613:
	s_or_b64 exec, exec, s[86:87]
	s_nop 5
	v_max_f32_e32 v0, v49, v49
	v_max_f32_e32 v1, v48, v48
	v_max_f32_e32 v0, v1, v0
	v_max3_f32 v0, v0, v50, v51
	v_max3_f32 v0, v0, v52, v53
	v_max3_f32 v0, v0, v54, v55
	v_max3_f32 v0, v0, v56, v57
	v_max3_f32 v0, v0, v58, v59
	v_max3_f32 v0, v0, v60, v61
	v_max3_f32 v0, v0, v62, v63
	v_max3_f32 v0, v0, v64, v65
	v_max3_f32 v0, v0, v66, v67
	v_max3_f32 v0, v0, v68, v69
	v_max3_f32 v0, v0, v70, v71
	v_max3_f32 v0, v0, v72, v73
	v_max3_f32 v0, v0, v74, v75
	v_max3_f32 v0, v0, v76, v77
	v_max3_f32 v0, v0, v78, v79
	v_mov_b32_e32 v1, v0
	v_mov_b32_e32 v225, v0
	s_nop 1
	v_permlane32_swap_b32_e32 v1, v225
	v_max3_f32 v0, v160, v1, v225
	v_sub_f32_e32 v48, v48, v0
	v_sub_f32_e32 v49, v49, v0
	v_sub_f32_e32 v64, v64, v0
	v_sub_f32_e32 v65, v65, v0
	v_exp_f32_e32 v161, v48
	v_exp_f32_e32 v165, v49
	v_sub_f32_e32 v48, v50, v0
	v_sub_f32_e32 v49, v51, v0
	v_sub_f32_e32 v50, v66, v0
	v_sub_f32_e32 v51, v67, v0
	v_sub_f32_e32 v2, v160, v0
	v_exp_f32_e32 v163, v64
	v_exp_f32_e32 v167, v65
	v_exp_f32_e32 v160, v48
	v_exp_f32_e32 v164, v49
	v_exp_f32_e32 v162, v50
	v_exp_f32_e32 v166, v51
	v_exp_f32_e32 v2, v2
	v_add_f32_e32 v48, v164, v160
	v_add_f32_e32 v49, v165, v161
	v_add_f32_e32 v50, v166, v162
	v_add_f32_e32 v51, v167, v163
	s_nop 0
	v_add_f32_e32 v48, v50, v48
	v_add_f32_e32 v49, v51, v49
	v_mul_f32_e32 v46, v2, v46
	v_mul_f32_e32 v47, v2, v47
	v_add_f32_e32 v1, 0, v49
	v_sub_f32_e32 v50, v52, v0
	v_sub_f32_e32 v51, v53, v0
	v_sub_f32_e32 v52, v68, v0
	v_sub_f32_e32 v53, v69, v0
	v_exp_f32_e32 v169, v50
	v_exp_f32_e32 v171, v51
	v_exp_f32_e32 v168, v52
	v_exp_f32_e32 v170, v53
	v_sub_f32_e32 v52, v54, v0
	v_sub_f32_e32 v53, v55, v0
	v_sub_f32_e32 v54, v70, v0
	v_sub_f32_e32 v55, v71, v0
	v_exp_f32_e32 v138, v52
	v_add_f32_e32 v50, v170, v168
	v_add_f32_e32 v51, v171, v169
	v_exp_f32_e32 v139, v53
	v_pk_add_f32 v[50:51], v[50:51], v[50:51] op_sel_hi:[0,1]
	v_exp_f32_e32 v140, v54
	v_exp_f32_e32 v141, v55
	v_sub_f32_e32 v56, v56, v0
	v_sub_f32_e32 v57, v57, v0
	v_sub_f32_e32 v64, v72, v0
	v_sub_f32_e32 v65, v73, v0
	v_add_f32_e32 v49, v48, v1
	v_exp_f32_e32 v48, v56
	v_exp_f32_e32 v50, v57
	v_exp_f32_e32 v52, v64
	v_exp_f32_e32 v54, v65
	v_add_f32_e32 v53, v139, v138
	v_add_f32_e32 v55, v141, v140
	v_add_f32_e32 v56, v50, v48
	v_add_f32_e32 v57, v51, v49
	v_add_f32_e32 v64, v54, v52
	v_add_f32_e32 v65, v55, v53
	v_sub_f32_e32 v66, v74, v0
	v_sub_f32_e32 v67, v75, v0
	v_add_f32_e32 v56, v64, v56
	v_add_f32_e32 v57, v65, v57
	v_sub_f32_e32 v64, v58, v0
	v_sub_f32_e32 v65, v59, v0
	v_exp_f32_e32 v58, v66
	v_exp_f32_e32 v59, v64
	v_exp_f32_e32 v65, v65
	v_exp_f32_e32 v64, v67
	v_sub_f32_e32 v60, v60, v0
	v_sub_f32_e32 v61, v61, v0
	v_sub_f32_e32 v68, v76, v0
	v_sub_f32_e32 v69, v77, v0
	v_pk_add_f32 v[56:57], v[56:57], v[56:57] op_sel_hi:[0,1]
	v_add_f32_e32 v66, v64, v58
	v_add_f32_e32 v67, v65, v59
	v_exp_f32_e32 v51, v60
	v_pk_add_f32 v[66:67], v[66:67], v[66:67] op_sel_hi:[0,1]
	v_exp_f32_e32 v55, v61
	v_exp_f32_e32 v146, v68
	v_exp_f32_e32 v147, v69
	v_sub_f32_e32 v62, v62, v0
	v_sub_f32_e32 v63, v63, v0
	v_sub_f32_e32 v70, v78, v0
	v_sub_f32_e32 v71, v79, v0
	v_exp_f32_e32 v56, v62
	v_exp_f32_e32 v66, v63
	v_exp_f32_e32 v60, v70
	v_exp_f32_e32 v68, v71
	v_add_f32_e32 v61, v55, v51
	v_add_f32_e32 v69, v147, v146
	v_add_f32_e32 v62, v66, v56
	v_add_f32_e32 v63, v67, v57
	v_add_f32_e32 v70, v68, v60
	v_add_f32_e32 v71, v69, v61
	v_mul_f32_e32 v44, v2, v44
	v_mul_f32_e32 v45, v2, v45
	v_add_f32_e32 v62, v70, v62
	v_add_f32_e32 v63, v71, v63
	v_mul_f32_e32 v42, v2, v42
	v_mul_f32_e32 v43, v2, v43
	v_add_f32_e32 v1, v62, v63
	v_fmac_f32_e32 v1, v191, v2
	v_mul_f32_e32 v40, v2, v40
	v_mul_f32_e32 v41, v2, v41
	v_mul_f32_e32 v38, v2, v38
	v_mul_f32_e32 v39, v2, v39
	v_mul_f32_e32 v36, v2, v36
	v_mul_f32_e32 v37, v2, v37
	v_mul_f32_e32 v34, v2, v34
	v_mul_f32_e32 v35, v2, v35
	v_mul_f32_e32 v32, v2, v32
	v_mul_f32_e32 v33, v2, v33
	v_mul_f32_e32 v30, v2, v30
	v_mul_f32_e32 v31, v2, v31
	v_mul_f32_e32 v28, v2, v28
	v_mul_f32_e32 v29, v2, v29
	v_mul_f32_e32 v26, v2, v26
	v_mul_f32_e32 v27, v2, v27
	v_mul_f32_e32 v24, v2, v24
	v_mul_f32_e32 v25, v2, v25
	v_mul_f32_e32 v22, v2, v22
	v_mul_f32_e32 v23, v2, v23
	v_mul_f32_e32 v20, v2, v20
	v_mul_f32_e32 v21, v2, v21
	v_mul_f32_e32 v18, v2, v18
	v_mul_f32_e32 v19, v2, v19
	v_mul_f32_e32 v16, v2, v16
	v_mul_f32_e32 v17, v2, v17
	v_add_u32_e32 v2, v186, v130
	v_cvt_pk_bf16_f32 v70, v161, v165
	v_cvt_pk_bf16_f32 v74, v163, v167
	v_cvt_pk_bf16_f32 v71, v160, v164
	v_cvt_pk_bf16_f32 v75, v162, v166
	v_cvt_pk_bf16_f32 v73, v138, v139
	v_cvt_pk_bf16_f32 v77, v140, v141
	ds_read_b128 v[138:141], v2 offset:36608
	ds_read_b128 v[142:145], v2 offset:32064
	ds_read_b128 v[150:153], v2 offset:36672
	ds_read_b128 v[160:163], v2 offset:32000
	ds_read_b128 v[164:167], v2 offset:32032
	v_cvt_pk_bf16_f32 v72, v169, v171
	v_cvt_pk_bf16_f32 v76, v168, v170
	v_cvt_pk_bf16_f32 v48, v48, v50
	s_waitcnt lgkmcnt(1)
	v_mfma_f32_32x32x16_bf16 v[32:47], v[160:163], v[70:73], v[32:47]
	v_cvt_pk_bf16_f32 v49, v59, v65
	v_cvt_pk_bf16_f32 v53, v58, v64
	v_cvt_pk_bf16_f32 v50, v51, v55
	v_cvt_pk_bf16_f32 v51, v56, v66
	v_cvt_pk_bf16_f32 v55, v60, v68
	ds_read_b128 v[56:59], v2 offset:36640
	ds_read_b128 v[60:63], v2 offset:32096
	ds_read_b128 v[64:67], v2 offset:36704
	v_cvt_pk_bf16_f32 v52, v52, v54
	v_mfma_f32_32x32x16_bf16 v[16:31], v[138:141], v[70:73], v[16:31]
	v_cvt_pk_bf16_f32 v54, v146, v147
	v_mov_b32_e32 v191, v1
	v_mov_b32_e32 v160, v0
	v_mfma_f32_32x32x16_bf16 v[32:47], v[142:145], v[74:77], v[32:47]
	v_mfma_f32_32x32x16_bf16 v[16:31], v[150:153], v[74:77], v[16:31]
	s_waitcnt lgkmcnt(3)
	v_mfma_f32_32x32x16_bf16 v[32:47], v[164:167], v[48:51], v[32:47]
	s_waitcnt lgkmcnt(2)
	v_mfma_f32_32x32x16_bf16 v[16:31], v[56:59], v[48:51], v[16:31]
	s_waitcnt lgkmcnt(1)
	v_mfma_f32_32x32x16_bf16 v[32:47], v[60:63], v[52:55], v[32:47]
	s_waitcnt lgkmcnt(0)
	v_mfma_f32_32x32x16_bf16 v[16:31], v[64:67], v[52:55], v[16:31]

; #define MFMA(a, b, c) __builtin_amdgcn_mfma_f32_32x32x16_bf16((a), (b), (c), 0, 0, 0)
; DI float fexp2(float x) { return __builtin_amdgcn_exp2f(x); }
; template <int TYPE>
; DI void attn_item(KargPtr p, int b, int h, int qb, unsigned char* smem) {
;     ...
;                 float mx = s0[0];
; #pragma unroll
;                 for (int i = 1; i < 16; ++i) mx = fmaxf(mx, s0[i]);
; #pragma unroll
;                 for (int i = 0; i < 16; ++i) mx = fmaxf(mx, s1[i]);
;                 mx = fmaxf(mx, __shfl_xor(mx, 32));
;                 const float mnew = fmaxf(m, mx);
;                 const float alpha = fexp2(m - mnew);
;                 m = mnew;
;                 float ps = 0.f;
; #pragma unroll
;                 for (int i = 0; i < 16; i += 2) {
;                     const f32x2_t mm = {mnew, mnew};
;                     const f32x2_t d0 = (f32x2_t){s0[i], s0[i + 1]} - mm, d1 = (f32x2_t){s1[i], s1[i + 1]} - mm;
;                     s0[i] = fexp2(d0[0]); s0[i + 1] = fexp2(d0[1]); s1[i] = fexp2(d1[0]); s1[i + 1] = fexp2(d1[1]);
;                     ps += (s0[i] + s0[i + 1]) + (s1[i] + s1[i + 1]);
;                 }
;                 lsum = lsum * alpha + ps;
; #pragma unroll
;                 for (int i = 0; i < 16; ++i) { o0[i] *= alpha; o1[i] *= alpha; }
;     ...
; #pragma unroll
;             for (int s2 = 0; s2 < 2; ++s2) {
;                 unsigned pk0[4], pk1[4];
; #pragma unroll
;                 for (int j = 0; j < 4; ++j) { pk0[j] = pack_bf16(s0[8 * s2 + 2 * j], s0[8 * s2 + 2 * j + 1]); pk1[j] = pack_bf16(s1[8 * s2 + 2 * j], s1[8 * s2 + 2 * j + 1]); }
;                 const uint4 u0 = make_uint4(pk0[0], pk0[1], pk0[2], pk0[3]), u1 = make_uint4(pk1[0], pk1[1], pk1[2], pk1[3]);
;                 const bf16x8 pf0 = __builtin_bit_cast(bf16x8, u0), pf1 = __builtin_bit_cast(bf16x8, u1);
;                 const bf16x8 v00 = *(const bf16x8*)(vb + r * VROWB + (16 * s2 + 8 * hh) * 2);
;                 const bf16x8 v01 = *(const bf16x8*)(vb + (32 + r) * VROWB + (16 * s2 + 8 * hh) * 2);
;                 const bf16x8 v10 = *(const bf16x8*)(vb + r * VROWB + (32 + 16 * s2 + 8 * hh) * 2);
;                 const bf16x8 v11 = *(const bf16x8*)(vb + (32 + r) * VROWB + (32 + 16 * s2 + 8 * hh) * 2);
;                 o0 = MFMA(v00, pf0, o0); o1 = MFMA(v01, pf0, o1);
;                 o0 = MFMA(v10, pf1, o0); o1 = MFMA(v11, pf1, o1);
;             }
.LBB0_625:
	s_or_b64 exec, exec, s[86:87]
	s_nop 5
	v_max_f32_e32 v0, v49, v49
	v_max_f32_e32 v1, v48, v48
	v_max_f32_e32 v0, v1, v0
	v_max3_f32 v0, v0, v50, v51
	v_max3_f32 v0, v0, v52, v53
	v_max3_f32 v0, v0, v54, v55
	v_max3_f32 v0, v0, v56, v57
	v_max3_f32 v0, v0, v58, v59
	v_max3_f32 v0, v0, v60, v61
	v_max3_f32 v0, v0, v62, v63
	v_max3_f32 v0, v0, v64, v65
	v_max3_f32 v0, v0, v66, v67
	v_max3_f32 v0, v0, v68, v69
	v_max3_f32 v0, v0, v70, v71
	v_max3_f32 v0, v0, v72, v73
	v_max3_f32 v0, v0, v74, v75
	v_max3_f32 v0, v0, v76, v77
	v_max3_f32 v0, v0, v78, v79
	v_mov_b32_e32 v1, v0
	v_mov_b32_e32 v225, v0
	s_nop 1
	v_permlane32_swap_b32_e32 v1, v225
	v_max3_f32 v0, v160, v1, v225
	v_sub_f32_e32 v48, v48, v0
	v_sub_f32_e32 v49, v49, v0
	v_sub_f32_e32 v64, v64, v0
	v_sub_f32_e32 v65, v65, v0
	v_exp_f32_e32 v161, v48
	v_exp_f32_e32 v165, v49
	v_sub_f32_e32 v48, v50, v0
	v_sub_f32_e32 v49, v51, v0
	v_sub_f32_e32 v50, v66, v0
	v_sub_f32_e32 v51, v67, v0
	v_sub_f32_e32 v2, v160, v0
	v_exp_f32_e32 v163, v64
	v_exp_f32_e32 v167, v65
	v_exp_f32_e32 v160, v48
	v_exp_f32_e32 v164, v49
	v_exp_f32_e32 v162, v50
	v_exp_f32_e32 v166, v51
	v_exp_f32_e32 v2, v2
	v_add_f32_e32 v48, v164, v160
	v_add_f32_e32 v49, v165, v161
	v_add_f32_e32 v50, v166, v162
	v_add_f32_e32 v51, v167, v163
	s_nop 0
	v_add_f32_e32 v48, v50, v48
	v_add_f32_e32 v49, v51, v49
	v_mul_f32_e32 v46, v2, v46
	v_mul_f32_e32 v47, v2, v47
	v_add_f32_e32 v1, 0, v49
	v_sub_f32_e32 v50, v52, v0
	v_sub_f32_e32 v51, v53, v0
	v_sub_f32_e32 v52, v68, v0
	v_sub_f32_e32 v53, v69, v0
	v_exp_f32_e32 v169, v50
	v_exp_f32_e32 v171, v51
	v_exp_f32_e32 v168, v52
	v_exp_f32_e32 v170, v53
	v_sub_f32_e32 v52, v54, v0
	v_sub_f32_e32 v53, v55, v0
	v_sub_f32_e32 v54, v70, v0
	v_sub_f32_e32 v55, v71, v0
	v_exp_f32_e32 v138, v52
	v_add_f32_e32 v50, v170, v168
	v_add_f32_e32 v51, v171, v169
	v_exp_f32_e32 v139, v53
	v_pk_add_f32 v[50:51], v[50:51], v[50:51] op_sel_hi:[0,1]
	v_exp_f32_e32 v140, v54
	v_exp_f32_e32 v141, v55
	v_sub_f32_e32 v56, v56, v0
	v_sub_f32_e32 v57, v57, v0
	v_sub_f32_e32 v64, v72, v0
	v_sub_f32_e32 v65, v73, v0
	v_add_f32_e32 v49, v48, v1
	v_exp_f32_e32 v48, v56
	v_exp_f32_e32 v50, v57
	v_exp_f32_e32 v52, v64
	v_exp_f32_e32 v54, v65
	v_add_f32_e32 v53, v139, v138
	v_add_f32_e32 v55, v141, v140
	v_add_f32_e32 v56, v50, v48
	v_add_f32_e32 v57, v51, v49
	v_add_f32_e32 v64, v54, v52
	v_add_f32_e32 v65, v55, v53
	v_sub_f32_e32 v66, v74, v0
	v_sub_f32_e32 v67, v75, v0
	v_add_f32_e32 v56, v64, v56
	v_add_f32_e32 v57, v65, v57
	v_sub_f32_e32 v64, v58, v0
	v_sub_f32_e32 v65, v59, v0
	v_exp_f32_e32 v58, v66
	v_exp_f32_e32 v59, v64
	v_exp_f32_e32 v65, v65
	v_exp_f32_e32 v64, v67
	v_sub_f32_e32 v60, v60, v0
	v_sub_f32_e32 v61, v61, v0
	v_sub_f32_e32 v68, v76, v0
	v_sub_f32_e32 v69, v77, v0
	v_pk_add_f32 v[56:57], v[56:57], v[56:57] op_sel_hi:[0,1]
	v_add_f32_e32 v66, v64, v58
	v_add_f32_e32 v67, v65, v59
	v_exp_f32_e32 v51, v60
	v_pk_add_f32 v[66:67], v[66:67], v[66:67] op_sel_hi:[0,1]
	v_exp_f32_e32 v55, v61
	v_exp_f32_e32 v146, v68
	v_exp_f32_e32 v147, v69
	v_sub_f32_e32 v62, v62, v0
	v_sub_f32_e32 v63, v63, v0
	v_sub_f32_e32 v70, v78, v0
	v_sub_f32_e32 v71, v79, v0
	v_exp_f32_e32 v56, v62
	v_exp_f32_e32 v66, v63
	v_exp_f32_e32 v60, v70
	v_exp_f32_e32 v68, v71
	v_add_f32_e32 v61, v55, v51
	v_add_f32_e32 v69, v147, v146
	v_add_f32_e32 v62, v66, v56
	v_add_f32_e32 v63, v67, v57
	v_add_f32_e32 v70, v68, v60
	v_add_f32_e32 v71, v69, v61
	v_mul_f32_e32 v44, v2, v44
	v_mul_f32_e32 v45, v2, v45
	v_add_f32_e32 v62, v70, v62
	v_add_f32_e32 v63, v71, v63
	v_mul_f32_e32 v42, v2, v42
	v_mul_f32_e32 v43, v2, v43
	v_add_f32_e32 v1, v62, v63
	v_fmac_f32_e32 v1, v191, v2
	v_mul_f32_e32 v40, v2, v40
	v_mul_f32_e32 v41, v2, v41
	v_mul_f32_e32 v38, v2, v38
	v_mul_f32_e32 v39, v2, v39
	v_mul_f32_e32 v36, v2, v36
	v_mul_f32_e32 v37, v2, v37
	v_mul_f32_e32 v34, v2, v34
	v_mul_f32_e32 v35, v2, v35
	v_mul_f32_e32 v32, v2, v32
	v_mul_f32_e32 v33, v2, v33
	v_mul_f32_e32 v30, v2, v30
	v_mul_f32_e32 v31, v2, v31
	v_mul_f32_e32 v28, v2, v28
	v_mul_f32_e32 v29, v2, v29
	v_mul_f32_e32 v26, v2, v26
	v_mul_f32_e32 v27, v2, v27
	v_mul_f32_e32 v24, v2, v24
	v_mul_f32_e32 v25, v2, v25
	v_mul_f32_e32 v22, v2, v22
	v_mul_f32_e32 v23, v2, v23
	v_mul_f32_e32 v20, v2, v20
	v_mul_f32_e32 v21, v2, v21
	v_mul_f32_e32 v18, v2, v18
	v_mul_f32_e32 v19, v2, v19
	v_mul_f32_e32 v16, v2, v16
	v_mul_f32_e32 v17, v2, v17
	v_add_u32_e32 v2, v186, v130
	v_cvt_pk_bf16_f32 v70, v161, v165
	v_cvt_pk_bf16_f32 v74, v163, v167
	v_cvt_pk_bf16_f32 v71, v160, v164
	v_cvt_pk_bf16_f32 v75, v162, v166
	v_cvt_pk_bf16_f32 v73, v138, v139
	v_cvt_pk_bf16_f32 v77, v140, v141
	ds_read_b128 v[138:141], v2 offset:15872
	ds_read_b128 v[142:145], v2 offset:11328
	ds_read_b128 v[150:153], v2 offset:15936
	ds_read_b128 v[160:163], v2 offset:11264
	ds_read_b128 v[164:167], v2 offset:11296
	v_cvt_pk_bf16_f32 v72, v169, v171
	v_cvt_pk_bf16_f32 v76, v168, v170
	v_cvt_pk_bf16_f32 v48, v48, v50
	s_waitcnt lgkmcnt(1)
	v_mfma_f32_32x32x16_bf16 v[32:47], v[160:163], v[70:73], v[32:47]
	v_cvt_pk_bf16_f32 v49, v59, v65
	v_cvt_pk_bf16_f32 v53, v58, v64
	v_cvt_pk_bf16_f32 v50, v51, v55
	v_cvt_pk_bf16_f32 v51, v56, v66
	v_cvt_pk_bf16_f32 v55, v60, v68
	ds_read_b128 v[56:59], v2 offset:15904
	ds_read_b128 v[60:63], v2 offset:11360
	ds_read_b128 v[64:67], v2 offset:15968
	v_cvt_pk_bf16_f32 v52, v52, v54
	v_mfma_f32_32x32x16_bf16 v[16:31], v[138:141], v[70:73], v[16:31]
	v_cvt_pk_bf16_f32 v54, v146, v147
	v_mov_b32_e32 v191, v1
	v_mov_b32_e32 v160, v0
	v_mfma_f32_32x32x16_bf16 v[32:47], v[142:145], v[74:77], v[32:47]
	v_mfma_f32_32x32x16_bf16 v[16:31], v[150:153], v[74:77], v[16:31]
	s_waitcnt lgkmcnt(3)
	v_mfma_f32_32x32x16_bf16 v[32:47], v[164:167], v[48:51], v[32:47]
	s_waitcnt lgkmcnt(2)
	v_mfma_f32_32x32x16_bf16 v[16:31], v[56:59], v[48:51], v[16:31]
	s_waitcnt lgkmcnt(1)
	v_mfma_f32_32x32x16_bf16 v[32:47], v[60:63], v[52:55], v[32:47]
	s_waitcnt lgkmcnt(0)
	v_mfma_f32_32x32x16_bf16 v[16:31], v[64:67], v[52:55], v[16:31]
